# GQA pipelined loop v3: ps adds and l update moved under PV MFMAs, cvts spread
# speedup vs baseline: 1.0019x; 1.0019x over previous
; __device__ __forceinline__ int crow(int r, int hi) { return (r & 3) + 8 * (r >> 2) + 4 * hi; }
; template <int DQK, bool NA>
; __device__ __forceinline__ void attn_unit(const UnitP& P, char* lds) {
;     ...
;     const int qgrow = P.qgrow0 + (wid >> 1), qc = (wid & 1) * 32 + r32;
;     const int r0w = min(max(qgrow - 4, 0), 24), c0 = min(max(qc - 8, 0), 48);
;     DMA(0, 0); asm volatile("s_waitcnt vmcnt(0)" ::: "memory"); __syncthreads();
;     for (int t = 0; t < P.NT; ++t) {
;         if (t + 1 < P.NT) DMA(t + 1, (t + 1) & 1);
;         bool act = true;
;         if constexpr (NA) act = (t >= P.nlat) || ((unsigned)(P.krow0 + t - r0w) < 8u);
;         if (act) {
;             const char* Kb = K_lds + (t & 1) * SHM_K;
;             f32x16 p0, p1;
; #pragma unroll
;             for (int r = 0; r < 16; ++r) { p0[r] = 0.f; p1[r] = 0.f; }
; #pragma unroll
;             for (int d0 = 0; d0 < NQ; ++d0) { const int cb = (d0 * 16 + hi * 8) * 2;
;                 const bf16x8 b0 = *reinterpret_cast<const bf16x8*>(Kb + KSWZ(r32, cb));
;                 const bf16x8 b1 = *reinterpret_cast<const bf16x8*>(Kb + KSWZ(32 + r32, cb));
;                 p0 = __builtin_amdgcn_mfma_f32_32x32x16_bf16(b0, qr[d0], p0, 0, 0, 0);
;                 p1 = __builtin_amdgcn_mfma_f32_32x32x16_bf16(b1, qr[d0], p1, 0, 0, 0); }
;     ...
; #pragma unroll
;             for (int r = 0; r < 16; ++r) { p0[r] = __builtin_amdgcn_exp2f(fmaf(p0[r], P.C, mnC)); p1[r] = __builtin_amdgcn_exp2f(fmaf(p1[r], P.C, mnC)); ps += p0[r] + p1[r]; }
;             { auto rr = __builtin_amdgcn_permlane32_swap(__float_as_uint(ps), __float_as_uint(ps), false, false);
;               ps = __uint_as_float(rr[0]) + __uint_as_float(rr[1]); }
;             l_reg = l_reg * alpha + ps;
;             if (__any(alpha < 1.f)) { if (hi == 0) al_l[r32] = alpha; asm volatile("s_waitcnt lgkmcnt(0)" ::: "memory");
; #pragma unroll
;                 for (int r = 0; r < 16; ++r) { const float a = al_l[crow(r, hi)];
; #pragma unroll
;                     for (int d = 0; d < 4; ++d) o[d][r] *= a; } }
;             bf16x8 pa0, pa1, pa2, pa3;
;     ...
;             PK4(p0, 0, pa0); PK4(p0, 8, pa1); PK4(p1, 0, pa2); PK4(p1, 8, pa3);
.Lgqa_loop:
	s_and_b32 s28, s16, 1
	s_mul_i32 s28, s28, 0x6000
	v_add_u32_e32 v0, s28, v144
	v_add_u32_e32 v154, v0, v152
	v_add_u32_e32 v155, v0, v151
	v_add_u32_e32 v156, v0, v150
	v_add_u32_e32 v157, v0, v149
	v_add_u32_e32 v194, v0, v148
	v_add_u32_e32 v195, v0, v147
	v_add_u32_e32 v244, v0, v146
	v_add_u32_e32 v245, v0, v145
	ds_read_b128 v[218:221], v154 offset:32768
	ds_read_b128 v[222:225], v155 offset:32768
	ds_read_b128 v[226:229], v156 offset:32768
	ds_read_b128 v[190:193], v157 offset:32768
	s_add_i32 s27, s16, 1
	s_cmp_lt_u32 s27, 32
	s_cselect_b32 s8, 0, 0xffffffe0
	s_cselect_b32 s9, s72, s19
	s_add_i32 s8, s8, s27
	s_lshl_b32 s8, s8, 6
	s_add_i32 s8, s8, s9
	s_mulk_i32 s8, 0x2e40
	s_ashr_i32 s9, s8, 31
	s_lshl_b64 s[8:9], s[8:9], 1
	s_bitcmp1_b32 s16, 0
	s_cselect_b32 s28, 0, 0x6000
	s_add_i32 s28, s10, s28
	s_add_i32 m0, s28, 0x8000
	v_lshl_add_u64 v[172:173], v[132:133], 0, s[8:9]
	global_load_lds_dwordx4 v[172:173], off
	s_add_i32 m0, s28, 0x8400
	v_lshl_add_u64 v[172:173], v[134:135], 0, s[8:9]
	global_load_lds_dwordx4 v[172:173], off
	s_cmp_lt_u32 s16, 32
	s_cselect_b32 s8, 0, 0xffffffe0
	s_cselect_b32 s9, s72, s19
	s_add_i32 s8, s8, s16
	s_lshl_b32 s8, s8, 6
	s_add_i32 s8, s8, s9
	s_mulk_i32 s8, 0x2e40
	s_ashr_i32 s9, s8, 31
	s_lshl_b64 s[8:9], s[8:9], 1
	s_and_b32 s28, s26, 0x4000
	s_add_i32 s28, s10, s28
	v_lshl_add_u64 v[172:173], v[136:137], 0, s[8:9]
	s_mov_b32 m0, s28
	s_nop 0
	global_load_lds_dwordx4 v[172:173], off
	s_add_i32 m0, s28, 0x400
	v_lshl_add_u64 v[172:173], v[172:173], 0, s[40:41]
	global_load_lds_dwordx4 v[172:173], off
	v_fmamk_f32 v66, v66, 0x3e0293ee, v153
	v_fmamk_f32 v82, v82, 0x3e0293ee, v153
	v_fmamk_f32 v67, v67, 0x3e0293ee, v153
	v_fmamk_f32 v83, v83, 0x3e0293ee, v153
	s_waitcnt lgkmcnt(3)
	v_mfma_f32_32x32x16_bf16 v[174:189], v[218:221], v[126:129], 0
	ds_read_b128 v[218:221], v154 offset:40960
	v_exp_f32_e32 v66, v66
	v_exp_f32_e32 v82, v82
	v_fmamk_f32 v68, v68, 0x3e0293ee, v153
	v_fmamk_f32 v84, v84, 0x3e0293ee, v153
	s_waitcnt lgkmcnt(3)
	v_mfma_f32_32x32x16_bf16 v[174:189], v[222:225], v[122:125], v[174:189]
	ds_read_b128 v[222:225], v155 offset:40960
	v_exp_f32_e32 v67, v67
	v_exp_f32_e32 v83, v83
	v_fmamk_f32 v69, v69, 0x3e0293ee, v153
	v_fmamk_f32 v85, v85, 0x3e0293ee, v153
	s_waitcnt lgkmcnt(3)
	v_mfma_f32_32x32x16_bf16 v[174:189], v[226:229], v[118:121], v[174:189]
	ds_read_b128 v[226:229], v194 offset:32768
	v_exp_f32_e32 v68, v68
	v_exp_f32_e32 v84, v84
	v_fmamk_f32 v70, v70, 0x3e0293ee, v153
	v_fmamk_f32 v86, v86, 0x3e0293ee, v153
	s_waitcnt lgkmcnt(3)
	v_mfma_f32_32x32x16_bf16 v[174:189], v[190:193], v[114:117], v[174:189]
	ds_read_b128 v[190:193], v195 offset:32768
	v_exp_f32_e32 v69, v69
	v_exp_f32_e32 v85, v85
	v_fmamk_f32 v71, v71, 0x3e0293ee, v153
	v_fmamk_f32 v87, v87, 0x3e0293ee, v153
	s_waitcnt lgkmcnt(3)
	v_mfma_f32_32x32x16_bf16 v[202:217], v[218:221], v[126:129], 0
	ds_read_b128 v[218:221], v244 offset:32768
	v_exp_f32_e32 v70, v70
	v_exp_f32_e32 v86, v86
	v_fmamk_f32 v72, v72, 0x3e0293ee, v153
	v_fmamk_f32 v88, v88, 0x3e0293ee, v153
	s_waitcnt lgkmcnt(3)
	v_mfma_f32_32x32x16_bf16 v[202:217], v[222:225], v[122:125], v[202:217]
	ds_read_b128 v[222:225], v245 offset:32768
	v_exp_f32_e32 v71, v71
	v_exp_f32_e32 v87, v87
	v_fmamk_f32 v73, v73, 0x3e0293ee, v153
	v_fmamk_f32 v89, v89, 0x3e0293ee, v153
	s_waitcnt lgkmcnt(3)
	v_mfma_f32_32x32x16_bf16 v[174:189], v[226:229], v[110:113], v[174:189]
	ds_read_b128 v[226:229], v156 offset:40960
	v_exp_f32_e32 v72, v72
	v_exp_f32_e32 v88, v88
	v_fmamk_f32 v74, v74, 0x3e0293ee, v153
	v_fmamk_f32 v90, v90, 0x3e0293ee, v153
	s_waitcnt lgkmcnt(3)
	v_mfma_f32_32x32x16_bf16 v[174:189], v[190:193], v[106:109], v[174:189]
	ds_read_b128 v[190:193], v157 offset:40960
	v_exp_f32_e32 v73, v73
	v_exp_f32_e32 v89, v89
	v_fmamk_f32 v75, v75, 0x3e0293ee, v153
	v_fmamk_f32 v91, v91, 0x3e0293ee, v153
	s_waitcnt lgkmcnt(3)
	v_mfma_f32_32x32x16_bf16 v[174:189], v[218:221], v[102:105], v[174:189]
	ds_read_b128 v[218:221], v194 offset:40960
	v_exp_f32_e32 v74, v74
	v_exp_f32_e32 v90, v90
	v_fmamk_f32 v76, v76, 0x3e0293ee, v153
	v_fmamk_f32 v92, v92, 0x3e0293ee, v153
	v_cvt_pk_bf16_f32 v158, v66, v67
	s_waitcnt lgkmcnt(3)
	v_mfma_f32_32x32x16_bf16 v[174:189], v[222:225], v[98:101], v[174:189]
	ds_read_b128 v[222:225], v195 offset:40960
	v_exp_f32_e32 v75, v75
	v_exp_f32_e32 v91, v91
	v_fmamk_f32 v77, v77, 0x3e0293ee, v153
	v_fmamk_f32 v93, v93, 0x3e0293ee, v153
	v_cvt_pk_bf16_f32 v159, v68, v69
	s_waitcnt lgkmcnt(3)
	v_mfma_f32_32x32x16_bf16 v[202:217], v[226:229], v[118:121], v[202:217]
	ds_read_b128 v[226:229], v244 offset:40960
	v_exp_f32_e32 v76, v76
	v_exp_f32_e32 v92, v92
	v_fmamk_f32 v78, v78, 0x3e0293ee, v153
	v_fmamk_f32 v94, v94, 0x3e0293ee, v153
	v_cvt_pk_bf16_f32 v160, v70, v71
	s_waitcnt lgkmcnt(3)
	v_mfma_f32_32x32x16_bf16 v[202:217], v[190:193], v[114:117], v[202:217]
	ds_read_b128 v[190:193], v245 offset:40960
	v_exp_f32_e32 v77, v77
	v_exp_f32_e32 v93, v93
	v_fmamk_f32 v79, v79, 0x3e0293ee, v153
	v_fmamk_f32 v95, v95, 0x3e0293ee, v153
	v_cvt_pk_bf16_f32 v161, v72, v73
	s_waitcnt lgkmcnt(3)
	v_mfma_f32_32x32x16_bf16 v[202:217], v[218:221], v[110:113], v[202:217]
	v_exp_f32_e32 v78, v78
	v_exp_f32_e32 v94, v94
	v_fmamk_f32 v80, v80, 0x3e0293ee, v153
	v_fmamk_f32 v96, v96, 0x3e0293ee, v153
	v_cvt_pk_bf16_f32 v166, v82, v83
	s_waitcnt lgkmcnt(2)
	v_mfma_f32_32x32x16_bf16 v[202:217], v[222:225], v[106:109], v[202:217]
	v_exp_f32_e32 v79, v79
	v_exp_f32_e32 v95, v95
	v_fmamk_f32 v81, v81, 0x3e0293ee, v153
	v_fmamk_f32 v97, v97, 0x3e0293ee, v153
	v_cvt_pk_bf16_f32 v167, v84, v85
	s_waitcnt lgkmcnt(1)
; template <int D0> __device__ __forceinline__ void pv_one(f32x16& od, int vb, bf16x8 pa0, bf16x8 pa1, bf16x8 pa2, bf16x8 pa3) {
;     const s16x4 l0 = tr_read<v_rd_off(D0, 0, 0)>(vb), h0 = tr_read<v_rd_off(D0, 0, 1)>(vb), l1 = tr_read<v_rd_off(D0, 1, 0)>(vb), h1 = tr_read<v_rd_off(D0, 1, 1)>(vb);
;     const s16x4 l2 = tr_read<v_rd_off(D0, 2, 0)>(vb), h2 = tr_read<v_rd_off(D0, 2, 1)>(vb), l3 = tr_read<v_rd_off(D0, 3, 0)>(vb), h3 = tr_read<v_rd_off(D0, 3, 1)>(vb);
; template <int DQK, bool NA>
; __device__ __forceinline__ void attn_unit(const UnitP& P, char* lds) {
;     ...
;             float pmax = p0[0];
; #pragma unroll
;             for (int r = 1; r < 16; ++r) pmax = fmaxf(pmax, p0[r]);
; #pragma unroll
;             for (int r = 0; r < 16; ++r) pmax = fmaxf(pmax, p1[r]);
;             { auto rr = __builtin_amdgcn_permlane32_swap(__float_as_uint(pmax), __float_as_uint(pmax), false, false);
;               pmax = fmaxf(__uint_as_float(rr[0]), __uint_as_float(rr[1])); }
;             float mn, alpha;
;             if (__all(pmax - m_reg <= P.thr_raw)) { mn = m_reg; alpha = 1.f; }
;             else { mn = fmaxf(m_reg, pmax); alpha = __builtin_amdgcn_exp2f((m_reg - mn) * P.C); m_reg = mn; }
;             const float mnC = -mn * P.C;
;             float ps = 0.f;
; #pragma unroll
;             for (int r = 0; r < 16; ++r) { p0[r] = __builtin_amdgcn_exp2f(fmaf(p0[r], P.C, mnC)); p1[r] = __builtin_amdgcn_exp2f(fmaf(p1[r], P.C, mnC)); ps += p0[r] + p1[r]; }
;             { auto rr = __builtin_amdgcn_permlane32_swap(__float_as_uint(ps), __float_as_uint(ps), false, false);
;               ps = __uint_as_float(rr[0]) + __uint_as_float(rr[1]); }
;             l_reg = l_reg * alpha + ps;
;             if (__any(alpha < 1.f)) { if (hi == 0) al_l[r32] = alpha; asm volatile("s_waitcnt lgkmcnt(0)" ::: "memory");
; #pragma unroll
;                 for (int r = 0; r < 16; ++r) { const float a = al_l[crow(r, hi)];
; #pragma unroll
;                     for (int d = 0; d < 4; ++d) o[d][r] *= a; } }
;             bf16x8 pa0, pa1, pa2, pa3;
;     ...
;             PK4(p0, 0, pa0); PK4(p0, 8, pa1); PK4(p1, 0, pa2); PK4(p1, 8, pa3);
;     ...
;             const int vb = vb0 + (t & 1) * SHM_V;
;             pv_one<0>(o[0], vb, pa0, pa1, pa2, pa3); pv_one<1>(o[1], vb, pa0, pa1, pa2, pa3); pv_one<2>(o[2], vb, pa0, pa1, pa2, pa3); pv_one<3>(o[3], vb, pa0, pa1, pa2, pa3);
	v_mfma_f32_32x32x16_bf16 v[202:217], v[226:229], v[102:105], v[202:217]
	v_exp_f32_e32 v80, v80
	v_exp_f32_e32 v96, v96
	v_cvt_pk_bf16_f32 v168, v86, v87
	s_waitcnt lgkmcnt(0)
	v_mfma_f32_32x32x16_bf16 v[202:217], v[190:193], v[98:101], v[202:217]
	v_exp_f32_e32 v81, v81
	v_exp_f32_e32 v97, v97
	v_cvt_pk_bf16_f32 v169, v88, v89
	s_add_i32 s27, s16, -1
	s_and_b32 s27, s27, 1
	v_lshl_add_u32 v246, s27, 14, v142
	ds_read_b64_tr_b16 v[218:219], v246 offset:0
	ds_read_b64_tr_b16 v[220:221], v246 offset:2048
	ds_read_b64_tr_b16 v[222:223], v246 offset:4096
	ds_read_b64_tr_b16 v[224:225], v246 offset:6144
	ds_read_b64_tr_b16 v[226:227], v246 offset:8192
	ds_read_b64_tr_b16 v[228:229], v246 offset:10240
	ds_read_b64_tr_b16 v[190:191], v246 offset:12288
	ds_read_b64_tr_b16 v[192:193], v246 offset:14336
	v_cvt_pk_bf16_f32 v162, v74, v75
	v_cvt_pk_bf16_f32 v163, v76, v77
	v_cvt_pk_bf16_f32 v164, v78, v79
	v_cvt_pk_bf16_f32 v170, v90, v91
	v_cvt_pk_bf16_f32 v171, v92, v93
	v_cvt_pk_bf16_f32 v172, v94, v95
	v_cvt_pk_bf16_f32 v165, v80, v81
	v_cvt_pk_bf16_f32 v173, v96, v97
	v_permlane32_swap_b32_e32 v158, v160
	v_permlane32_swap_b32_e32 v159, v161
	v_permlane32_swap_b32_e32 v166, v168
	v_permlane32_swap_b32_e32 v167, v169
	v_permlane32_swap_b32_e32 v162, v164
	v_permlane32_swap_b32_e32 v163, v165
	v_permlane32_swap_b32_e32 v170, v172
	v_permlane32_swap_b32_e32 v171, v173
	s_waitcnt lgkmcnt(6)
	v_mfma_f32_32x32x16_bf16 v[50:65], v[158:161], v[218:221], v[50:65]
	ds_read_b64_tr_b16 v[218:219], v246 offset:512
	ds_read_b64_tr_b16 v[220:221], v246 offset:2560
	v_add_f32_e32 v248, v66, v82
	v_add_f32_e32 v154, v67, v83
	v_add_f32_e32 v248, v248, v154
	v_add_f32_e32 v154, v68, v84
	v_max_f32_e32 v138, v174, v174
	v_max_f32_e32 v0, v175, v175
	v_max_f32_e32 v0, v138, v0
	s_waitcnt lgkmcnt(6)
	v_mfma_f32_32x32x16_bf16 v[50:65], v[162:165], v[222:225], v[50:65]
	ds_read_b64_tr_b16 v[222:223], v246 offset:4608
	ds_read_b64_tr_b16 v[224:225], v246 offset:6656
	v_add_f32_e32 v248, v248, v154
	v_add_f32_e32 v154, v69, v85
	v_add_f32_e32 v248, v248, v154
	v_add_f32_e32 v154, v70, v86
	v_max3_f32 v0, v0, v176, v177
	v_max3_f32 v0, v0, v178, v179
	v_max3_f32 v0, v0, v180, v181
	s_waitcnt lgkmcnt(6)
	v_mfma_f32_32x32x16_bf16 v[50:65], v[166:169], v[226:229], v[50:65]
	ds_read_b64_tr_b16 v[226:227], v246 offset:8704
	ds_read_b64_tr_b16 v[228:229], v246 offset:10752
	v_add_f32_e32 v248, v248, v154
	v_add_f32_e32 v154, v71, v87
	v_add_f32_e32 v248, v248, v154
	v_add_f32_e32 v154, v72, v88
	v_max3_f32 v0, v0, v182, v183
	v_max3_f32 v0, v0, v184, v185
	s_waitcnt lgkmcnt(6)
	v_mfma_f32_32x32x16_bf16 v[50:65], v[170:173], v[190:193], v[50:65]
	ds_read_b64_tr_b16 v[190:191], v246 offset:12800
	ds_read_b64_tr_b16 v[192:193], v246 offset:14848
	v_add_f32_e32 v248, v248, v154
	v_add_f32_e32 v154, v73, v89
	v_add_f32_e32 v248, v248, v154
	v_add_f32_e32 v154, v74, v90
	v_max3_f32 v0, v0, v186, v187
	v_max3_f32 v0, v0, v188, v189
	s_waitcnt lgkmcnt(6)
	v_mfma_f32_32x32x16_bf16 v[34:49], v[158:161], v[218:221], v[34:49]
	ds_read_b64_tr_b16 v[218:219], v246 offset:1024
	ds_read_b64_tr_b16 v[220:221], v246 offset:3072
	v_add_f32_e32 v248, v248, v154
	v_add_f32_e32 v154, v75, v91
	v_add_f32_e32 v248, v248, v154
	v_add_f32_e32 v154, v76, v92
	v_max3_f32 v0, v0, v202, v203
	v_max3_f32 v0, v0, v204, v205
	s_waitcnt lgkmcnt(6)
	v_mfma_f32_32x32x16_bf16 v[34:49], v[162:165], v[222:225], v[34:49]
	ds_read_b64_tr_b16 v[222:223], v246 offset:5120
	ds_read_b64_tr_b16 v[224:225], v246 offset:7168
	v_add_f32_e32 v248, v248, v154
	v_add_f32_e32 v154, v77, v93
	v_add_f32_e32 v248, v248, v154
	v_add_f32_e32 v154, v78, v94
	v_max3_f32 v0, v0, v206, v207
	v_max3_f32 v0, v0, v208, v209
	s_waitcnt lgkmcnt(6)
	v_mfma_f32_32x32x16_bf16 v[34:49], v[166:169], v[226:229], v[34:49]
	ds_read_b64_tr_b16 v[226:227], v246 offset:9216
	ds_read_b64_tr_b16 v[228:229], v246 offset:11264
	v_add_f32_e32 v248, v248, v154
	v_add_f32_e32 v154, v79, v95
	v_add_f32_e32 v248, v248, v154
	v_add_f32_e32 v154, v80, v96
	v_max3_f32 v0, v0, v210, v211
	v_max3_f32 v0, v0, v212, v213
	s_waitcnt lgkmcnt(6)
	v_mfma_f32_32x32x16_bf16 v[34:49], v[170:173], v[190:193], v[34:49]
	ds_read_b64_tr_b16 v[190:191], v246 offset:13312
	ds_read_b64_tr_b16 v[192:193], v246 offset:15360
	v_add_f32_e32 v248, v248, v154
	v_add_f32_e32 v154, v81, v97
	v_add_f32_e32 v248, v248, v154
	v_max3_f32 v0, v0, v214, v215
	v_max3_f32 v0, v0, v216, v217
	s_waitcnt lgkmcnt(6)
	v_mfma_f32_32x32x16_bf16 v[18:33], v[158:161], v[218:221], v[18:33]
	ds_read_b64_tr_b16 v[218:219], v246 offset:1536
	ds_read_b64_tr_b16 v[220:221], v246 offset:3584
	v_mov_b32_e32 v154, v248
	s_nop 1
	v_permlane32_swap_b32_e32 v248, v154
	v_add_f32_e32 v154, v248, v154
	v_fma_f32 v139, v139, v247, v154
	s_waitcnt lgkmcnt(6)
	v_mfma_f32_32x32x16_bf16 v[18:33], v[162:165], v[222:225], v[18:33]
	ds_read_b64_tr_b16 v[222:223], v246 offset:5632
	ds_read_b64_tr_b16 v[224:225], v246 offset:7680
	v_mov_b32_e32 v138, v0
	s_nop 1
	v_permlane32_swap_b32_e32 v0, v138
	v_max_f32_e32 v138, v138, v138
	v_max_f32_e32 v0, v0, v0
	s_waitcnt lgkmcnt(6)
	v_mfma_f32_32x32x16_bf16 v[18:33], v[166:169], v[226:229], v[18:33]
	ds_read_b64_tr_b16 v[226:227], v246 offset:9728
	ds_read_b64_tr_b16 v[228:229], v246 offset:11776
	v_max_f32_e32 v0, v0, v138
	v_sub_f32_e32 v138, v0, v143
	v_cmp_ge_f32_e32 vcc, s79, v138
	s_cmp_eq_u64 vcc, exec
	v_max_f32_e32 v138, v143, v143
	s_waitcnt lgkmcnt(6)
	v_mfma_f32_32x32x16_bf16 v[18:33], v[170:173], v[190:193], v[18:33]
	ds_read_b64_tr_b16 v[190:191], v246 offset:13824
	ds_read_b64_tr_b16 v[192:193], v246 offset:15872
	v_max_f32_e32 v0, v138, v0
	s_cselect_b64 vcc, -1, 0
	v_sub_f32_e32 v138, v143, v0
	v_cndmask_b32_e32 v143, v0, v143, vcc
	v_mul_f32_e32 v153, 0xbe0293ee, v143
	s_waitcnt lgkmcnt(6)
	v_mfma_f32_32x32x16_bf16 v[2:17], v[158:161], v[218:221], v[2:17]
	v_mul_f32_e32 v0, 0x3e0293ee, v138
	v_exp_f32_e32 v0, v0
	s_nop 0
	v_cndmask_b32_e64 v247, v0, 1.0, vcc
	v_mov_b64_e32 v[66:67], v[174:175]
	s_waitcnt lgkmcnt(4)
	v_mfma_f32_32x32x16_bf16 v[2:17], v[162:165], v[222:225], v[2:17]
	v_mov_b64_e32 v[68:69], v[176:177]
	v_mov_b64_e32 v[70:71], v[178:179]
	v_mov_b64_e32 v[72:73], v[180:181]
	v_mov_b64_e32 v[74:75], v[182:183]
	v_mov_b64_e32 v[76:77], v[184:185]
	s_waitcnt lgkmcnt(2)
	v_mfma_f32_32x32x16_bf16 v[2:17], v[166:169], v[226:229], v[2:17]
	v_mov_b64_e32 v[78:79], v[186:187]
	v_mov_b64_e32 v[80:81], v[188:189]
	v_mov_b64_e32 v[82:83], v[202:203]
	v_mov_b64_e32 v[84:85], v[204:205]
	v_mov_b64_e32 v[86:87], v[206:207]
	s_waitcnt lgkmcnt(0)
	v_mfma_f32_32x32x16_bf16 v[2:17], v[170:173], v[190:193], v[2:17]
	v_mov_b64_e32 v[88:89], v[208:209]
	v_mov_b64_e32 v[90:91], v[210:211]
	v_mov_b64_e32 v[92:93], v[212:213]
	v_mov_b64_e32 v[94:95], v[214:215]
	v_mov_b64_e32 v[96:97], v[216:217]
	v_cmp_gt_f32_e32 vcc, 1.0, v247
	s_cbranch_vccz .Lgqa_nors_loop
; __device__ __forceinline__ int crow(int r, int hi) { return (r & 3) + 8 * (r >> 2) + 4 * hi; }
; template <int DQK, bool NA>
; __device__ __forceinline__ void attn_unit(const UnitP& P, char* lds) {
;     ...
; #pragma unroll
;             for (int r = 0; r < 16; ++r) { p0[r] = __builtin_amdgcn_exp2f(fmaf(p0[r], P.C, mnC)); p1[r] = __builtin_amdgcn_exp2f(fmaf(p1[r], P.C, mnC)); ps += p0[r] + p1[r]; }
;             { auto rr = __builtin_amdgcn_permlane32_swap(__float_as_uint(ps), __float_as_uint(ps), false, false);
;               ps = __uint_as_float(rr[0]) + __uint_as_float(rr[1]); }
;             l_reg = l_reg * alpha + ps;
;             if (__any(alpha < 1.f)) { if (hi == 0) al_l[r32] = alpha; asm volatile("s_waitcnt lgkmcnt(0)" ::: "memory");
; #pragma unroll
;                 for (int r = 0; r < 16; ++r) { const float a = al_l[crow(r, hi)];
; #pragma unroll
;                     for (int d = 0; d < 4; ++d) o[d][r] *= a; } }
;             bf16x8 pa0, pa1, pa2, pa3;
;     ...
;             PK4(p0, 0, pa0); PK4(p0, 8, pa1); PK4(p1, 0, pa2); PK4(p1, 8, pa3);
;     ...
;             const int vb = vb0 + (t & 1) * SHM_V;
;             pv_one<0>(o[0], vb, pa0, pa1, pa2, pa3); pv_one<1>(o[1], vb, pa0, pa1, pa2, pa3); pv_one<2>(o[2], vb, pa0, pa1, pa2, pa3); pv_one<3>(o[3], vb, pa0, pa1, pa2, pa3);
;         }
;         asm volatile("s_waitcnt vmcnt(0)" ::: "memory");
;         __syncthreads();
	s_nop 7
	s_and_saveexec_b64 s[8:9], s[4:5]
	ds_write_b32 v131, v247 offset:128
	s_or_b64 exec, exec, s[8:9]
	s_waitcnt lgkmcnt(0)
	v_add_u32_e32 v0, s11, v130
	ds_read_b128 v[158:161], v0 offset:224
	ds_read_b128 v[162:165], v0 offset:192
	ds_read_b128 v[166:169], v0 offset:160
	ds_read_b128 v[170:173], v0 offset:128
	s_waitcnt lgkmcnt(0)
	v_pk_mul_f32 v[62:63], v[62:63], v[158:159]
	v_pk_mul_f32 v[58:59], v[58:59], v[162:163]
	v_pk_mul_f32 v[54:55], v[54:55], v[166:167]
	v_pk_mul_f32 v[64:65], v[64:65], v[160:161]
	v_pk_mul_f32 v[60:61], v[60:61], v[164:165]
	v_pk_mul_f32 v[56:57], v[56:57], v[168:169]
	v_pk_mul_f32 v[52:53], v[52:53], v[172:173]
	v_pk_mul_f32 v[50:51], v[50:51], v[170:171]
	v_pk_mul_f32 v[46:47], v[46:47], v[158:159]
	v_pk_mul_f32 v[42:43], v[42:43], v[162:163]
	v_pk_mul_f32 v[38:39], v[38:39], v[166:167]
	v_pk_mul_f32 v[48:49], v[48:49], v[160:161]
	v_pk_mul_f32 v[44:45], v[44:45], v[164:165]
	v_pk_mul_f32 v[40:41], v[40:41], v[168:169]
	v_pk_mul_f32 v[36:37], v[36:37], v[172:173]
	v_pk_mul_f32 v[34:35], v[34:35], v[170:171]
	v_pk_mul_f32 v[30:31], v[30:31], v[158:159]
	v_pk_mul_f32 v[26:27], v[26:27], v[162:163]
	v_pk_mul_f32 v[22:23], v[22:23], v[166:167]
	v_pk_mul_f32 v[32:33], v[32:33], v[160:161]
	v_pk_mul_f32 v[28:29], v[28:29], v[164:165]
	v_pk_mul_f32 v[24:25], v[24:25], v[168:169]
	v_pk_mul_f32 v[20:21], v[20:21], v[172:173]
	v_pk_mul_f32 v[18:19], v[18:19], v[170:171]
	v_pk_mul_f32 v[14:15], v[14:15], v[158:159]
	v_pk_mul_f32 v[10:11], v[10:11], v[162:163]
	v_pk_mul_f32 v[6:7], v[6:7], v[166:167]
	v_pk_mul_f32 v[16:17], v[16:17], v[160:161]
	v_pk_mul_f32 v[12:13], v[12:13], v[164:165]
	v_pk_mul_f32 v[8:9], v[8:9], v[168:169]
	v_pk_mul_f32 v[4:5], v[4:5], v[172:173]
	v_pk_mul_f32 v[2:3], v[2:3], v[170:171]
.Lgqa_nors_loop:
	s_add_i32 s16, s16, 1
	s_addk_i32 s26, 0x4000
	s_cmp_eq_u32 s16, 35
	s_waitcnt vmcnt(0)
	s_barrier
	s_cbranch_scc0 .Lgqa_loop
	s_cmp_lt_u32 s16, 32
	s_cselect_b32 s8, 0, 0xffffffe0
	s_cselect_b32 s9, s72, s19
	s_add_i32 s8, s8, s16
	s_lshl_b32 s8, s8, 6
	s_add_i32 s8, s8, s9
	s_mulk_i32 s8, 0x2e40
	s_ashr_i32 s9, s8, 31
	s_lshl_b64 s[8:9], s[8:9], 1
	s_and_b32 s28, s26, 0x4000
	s_add_i32 s28, s10, s28
	v_lshl_add_u64 v[172:173], v[136:137], 0, s[8:9]
	s_mov_b32 m0, s28
	s_nop 0
	global_load_lds_dwordx4 v[172:173], off
	s_add_i32 m0, s28, 0x400
	v_lshl_add_u64 v[172:173], v[172:173], 0, s[40:41]
	global_load_lds_dwordx4 v[172:173], off
	v_fmamk_f32 v66, v66, 0x3e0293ee, v153
	v_fmamk_f32 v82, v82, 0x3e0293ee, v153
	v_fmamk_f32 v67, v67, 0x3e0293ee, v153
	v_fmamk_f32 v83, v83, 0x3e0293ee, v153
	v_exp_f32_e32 v66, v66
	v_exp_f32_e32 v82, v82
	v_fmamk_f32 v68, v68, 0x3e0293ee, v153
	v_fmamk_f32 v84, v84, 0x3e0293ee, v153
	v_exp_f32_e32 v67, v67
	v_exp_f32_e32 v83, v83
	v_fmamk_f32 v69, v69, 0x3e0293ee, v153
	v_fmamk_f32 v85, v85, 0x3e0293ee, v153
	v_exp_f32_e32 v68, v68
	v_exp_f32_e32 v84, v84
	v_fmamk_f32 v70, v70, 0x3e0293ee, v153
	v_fmamk_f32 v86, v86, 0x3e0293ee, v153
	v_exp_f32_e32 v69, v69
	v_exp_f32_e32 v85, v85
	v_fmamk_f32 v71, v71, 0x3e0293ee, v153
	v_fmamk_f32 v87, v87, 0x3e0293ee, v153
	v_exp_f32_e32 v70, v70
	v_exp_f32_e32 v86, v86
	v_fmamk_f32 v72, v72, 0x3e0293ee, v153
	v_fmamk_f32 v88, v88, 0x3e0293ee, v153
	v_exp_f32_e32 v71, v71
	v_exp_f32_e32 v87, v87
	v_fmamk_f32 v73, v73, 0x3e0293ee, v153
	v_fmamk_f32 v89, v89, 0x3e0293ee, v153
	v_exp_f32_e32 v72, v72
	v_exp_f32_e32 v88, v88
	v_fmamk_f32 v74, v74, 0x3e0293ee, v153
	v_fmamk_f32 v90, v90, 0x3e0293ee, v153
	v_exp_f32_e32 v73, v73
	v_exp_f32_e32 v89, v89
	v_fmamk_f32 v75, v75, 0x3e0293ee, v153
	v_fmamk_f32 v91, v91, 0x3e0293ee, v153
	v_exp_f32_e32 v74, v74
	v_exp_f32_e32 v90, v90
	v_fmamk_f32 v76, v76, 0x3e0293ee, v153
	v_fmamk_f32 v92, v92, 0x3e0293ee, v153
	v_cvt_pk_bf16_f32 v158, v66, v67
	v_exp_f32_e32 v75, v75
	v_exp_f32_e32 v91, v91
	v_fmamk_f32 v77, v77, 0x3e0293ee, v153
	v_fmamk_f32 v93, v93, 0x3e0293ee, v153
	v_cvt_pk_bf16_f32 v159, v68, v69
	v_exp_f32_e32 v76, v76
	v_exp_f32_e32 v92, v92
	v_fmamk_f32 v78, v78, 0x3e0293ee, v153
	v_fmamk_f32 v94, v94, 0x3e0293ee, v153
	v_cvt_pk_bf16_f32 v160, v70, v71
	v_exp_f32_e32 v77, v77
	v_exp_f32_e32 v93, v93
	v_fmamk_f32 v79, v79, 0x3e0293ee, v153
	v_fmamk_f32 v95, v95, 0x3e0293ee, v153
	v_cvt_pk_bf16_f32 v161, v72, v73
	v_exp_f32_e32 v78, v78
	v_exp_f32_e32 v94, v94
	v_fmamk_f32 v80, v80, 0x3e0293ee, v153
	v_fmamk_f32 v96, v96, 0x3e0293ee, v153
	v_cvt_pk_bf16_f32 v166, v82, v83
	v_exp_f32_e32 v79, v79
	v_exp_f32_e32 v95, v95
	v_fmamk_f32 v81, v81, 0x3e0293ee, v153
	v_fmamk_f32 v97, v97, 0x3e0293ee, v153
	v_cvt_pk_bf16_f32 v167, v84, v85
	v_exp_f32_e32 v80, v80
	v_exp_f32_e32 v96, v96
	v_cvt_pk_bf16_f32 v168, v86, v87
	v_exp_f32_e32 v81, v81
	v_exp_f32_e32 v97, v97
	v_cvt_pk_bf16_f32 v169, v88, v89
	s_add_i32 s27, s16, -1
	s_and_b32 s27, s27, 1
	v_lshl_add_u32 v246, s27, 14, v142
	ds_read_b64_tr_b16 v[218:219], v246 offset:0
	ds_read_b64_tr_b16 v[220:221], v246 offset:2048
	ds_read_b64_tr_b16 v[222:223], v246 offset:4096
	ds_read_b64_tr_b16 v[224:225], v246 offset:6144
	ds_read_b64_tr_b16 v[226:227], v246 offset:8192
	ds_read_b64_tr_b16 v[228:229], v246 offset:10240
	ds_read_b64_tr_b16 v[190:191], v246 offset:12288
	ds_read_b64_tr_b16 v[192:193], v246 offset:14336
	v_cvt_pk_bf16_f32 v162, v74, v75
	v_cvt_pk_bf16_f32 v163, v76, v77
	v_cvt_pk_bf16_f32 v164, v78, v79
	v_cvt_pk_bf16_f32 v170, v90, v91
	v_cvt_pk_bf16_f32 v171, v92, v93
	v_cvt_pk_bf16_f32 v172, v94, v95
	v_cvt_pk_bf16_f32 v165, v80, v81
	v_cvt_pk_bf16_f32 v173, v96, v97
	v_permlane32_swap_b32_e32 v158, v160
	v_permlane32_swap_b32_e32 v159, v161
	v_permlane32_swap_b32_e32 v166, v168
	v_permlane32_swap_b32_e32 v167, v169
	v_permlane32_swap_b32_e32 v162, v164
	v_permlane32_swap_b32_e32 v163, v165
	v_permlane32_swap_b32_e32 v170, v172
	v_permlane32_swap_b32_e32 v171, v173
	s_waitcnt lgkmcnt(6)
; __device__ __forceinline__ int crow(int r, int hi) { return (r & 3) + 8 * (r >> 2) + 4 * hi; }
; template <int D0> __device__ __forceinline__ void pv_one(f32x16& od, int vb, bf16x8 pa0, bf16x8 pa1, bf16x8 pa2, bf16x8 pa3) {
;     const s16x4 l0 = tr_read<v_rd_off(D0, 0, 0)>(vb), h0 = tr_read<v_rd_off(D0, 0, 1)>(vb), l1 = tr_read<v_rd_off(D0, 1, 0)>(vb), h1 = tr_read<v_rd_off(D0, 1, 1)>(vb);
;     const s16x4 l2 = tr_read<v_rd_off(D0, 2, 0)>(vb), h2 = tr_read<v_rd_off(D0, 2, 1)>(vb), l3 = tr_read<v_rd_off(D0, 3, 0)>(vb), h3 = tr_read<v_rd_off(D0, 3, 1)>(vb);
;     asm volatile("s_waitcnt lgkmcnt(0)" ::: "memory"); __builtin_amdgcn_sched_barrier(0);
;     ...
;     od = __builtin_amdgcn_mfma_f32_32x32x16_bf16(pa0, PK(l0, h0), od, 0, 0, 0);
;     od = __builtin_amdgcn_mfma_f32_32x32x16_bf16(pa1, PK(l1, h1), od, 0, 0, 0);
;     od = __builtin_amdgcn_mfma_f32_32x32x16_bf16(pa2, PK(l2, h2), od, 0, 0, 0);
;     od = __builtin_amdgcn_mfma_f32_32x32x16_bf16(pa3, PK(l3, h3), od, 0, 0, 0);
; template <int DQK, bool NA>
; __device__ __forceinline__ void attn_unit(const UnitP& P, char* lds) {
;     ...
;             { auto rr = __builtin_amdgcn_permlane32_swap(__float_as_uint(ps), __float_as_uint(ps), false, false);
;               ps = __uint_as_float(rr[0]) + __uint_as_float(rr[1]); }
;             l_reg = l_reg * alpha + ps;
;             if (__any(alpha < 1.f)) { if (hi == 0) al_l[r32] = alpha; asm volatile("s_waitcnt lgkmcnt(0)" ::: "memory");
; #pragma unroll
;                 for (int r = 0; r < 16; ++r) { const float a = al_l[crow(r, hi)];
; #pragma unroll
;                     for (int d = 0; d < 4; ++d) o[d][r] *= a; } }
;             bf16x8 pa0, pa1, pa2, pa3;
;     ...
;             PK4(p0, 0, pa0); PK4(p0, 8, pa1); PK4(p1, 0, pa2); PK4(p1, 8, pa3);
;     ...
;             const int vb = vb0 + (t & 1) * SHM_V;
;             pv_one<0>(o[0], vb, pa0, pa1, pa2, pa3); pv_one<1>(o[1], vb, pa0, pa1, pa2, pa3); pv_one<2>(o[2], vb, pa0, pa1, pa2, pa3); pv_one<3>(o[3], vb, pa0, pa1, pa2, pa3);
;         }
;         asm volatile("s_waitcnt vmcnt(0)" ::: "memory");
;         __syncthreads();
	v_mfma_f32_32x32x16_bf16 v[50:65], v[158:161], v[218:221], v[50:65]
	ds_read_b64_tr_b16 v[218:219], v246 offset:512
	ds_read_b64_tr_b16 v[220:221], v246 offset:2560
	v_add_f32_e32 v248, v66, v82
	v_add_f32_e32 v154, v67, v83
	v_add_f32_e32 v248, v248, v154
	v_add_f32_e32 v154, v68, v84
	s_waitcnt lgkmcnt(6)
	v_mfma_f32_32x32x16_bf16 v[50:65], v[162:165], v[222:225], v[50:65]
	ds_read_b64_tr_b16 v[222:223], v246 offset:4608
	ds_read_b64_tr_b16 v[224:225], v246 offset:6656
	v_add_f32_e32 v248, v248, v154
	v_add_f32_e32 v154, v69, v85
	v_add_f32_e32 v248, v248, v154
	v_add_f32_e32 v154, v70, v86
	s_waitcnt lgkmcnt(6)
	v_mfma_f32_32x32x16_bf16 v[50:65], v[166:169], v[226:229], v[50:65]
	ds_read_b64_tr_b16 v[226:227], v246 offset:8704
	ds_read_b64_tr_b16 v[228:229], v246 offset:10752
	v_add_f32_e32 v248, v248, v154
	v_add_f32_e32 v154, v71, v87
	v_add_f32_e32 v248, v248, v154
	v_add_f32_e32 v154, v72, v88
	s_waitcnt lgkmcnt(6)
	v_mfma_f32_32x32x16_bf16 v[50:65], v[170:173], v[190:193], v[50:65]
	ds_read_b64_tr_b16 v[190:191], v246 offset:12800
	ds_read_b64_tr_b16 v[192:193], v246 offset:14848
	v_add_f32_e32 v248, v248, v154
	v_add_f32_e32 v154, v73, v89
	v_add_f32_e32 v248, v248, v154
	v_add_f32_e32 v154, v74, v90
	s_waitcnt lgkmcnt(6)
	v_mfma_f32_32x32x16_bf16 v[34:49], v[158:161], v[218:221], v[34:49]
	ds_read_b64_tr_b16 v[218:219], v246 offset:1024
	ds_read_b64_tr_b16 v[220:221], v246 offset:3072
	v_add_f32_e32 v248, v248, v154
	v_add_f32_e32 v154, v75, v91
	v_add_f32_e32 v248, v248, v154
	v_add_f32_e32 v154, v76, v92
	s_waitcnt lgkmcnt(6)
	v_mfma_f32_32x32x16_bf16 v[34:49], v[162:165], v[222:225], v[34:49]
	ds_read_b64_tr_b16 v[222:223], v246 offset:5120
	ds_read_b64_tr_b16 v[224:225], v246 offset:7168
	v_add_f32_e32 v248, v248, v154
	v_add_f32_e32 v154, v77, v93
	v_add_f32_e32 v248, v248, v154
	v_add_f32_e32 v154, v78, v94
	s_waitcnt lgkmcnt(6)
	v_mfma_f32_32x32x16_bf16 v[34:49], v[166:169], v[226:229], v[34:49]
	ds_read_b64_tr_b16 v[226:227], v246 offset:9216
	ds_read_b64_tr_b16 v[228:229], v246 offset:11264
	v_add_f32_e32 v248, v248, v154
	v_add_f32_e32 v154, v79, v95
	v_add_f32_e32 v248, v248, v154
	v_add_f32_e32 v154, v80, v96
	s_waitcnt lgkmcnt(6)
	v_mfma_f32_32x32x16_bf16 v[34:49], v[170:173], v[190:193], v[34:49]
	ds_read_b64_tr_b16 v[190:191], v246 offset:13312
	ds_read_b64_tr_b16 v[192:193], v246 offset:15360
	v_add_f32_e32 v248, v248, v154
	v_add_f32_e32 v154, v81, v97
	v_add_f32_e32 v248, v248, v154
	s_waitcnt lgkmcnt(6)
	v_mfma_f32_32x32x16_bf16 v[18:33], v[158:161], v[218:221], v[18:33]
	ds_read_b64_tr_b16 v[218:219], v246 offset:1536
	ds_read_b64_tr_b16 v[220:221], v246 offset:3584
	v_mov_b32_e32 v154, v248
	s_nop 1
	v_permlane32_swap_b32_e32 v248, v154
	v_add_f32_e32 v154, v248, v154
	v_fma_f32 v139, v139, v247, v154
	s_waitcnt lgkmcnt(6)
	v_mfma_f32_32x32x16_bf16 v[18:33], v[162:165], v[222:225], v[18:33]
	ds_read_b64_tr_b16 v[222:223], v246 offset:5632
	ds_read_b64_tr_b16 v[224:225], v246 offset:7680
	s_waitcnt lgkmcnt(6)
	v_mfma_f32_32x32x16_bf16 v[18:33], v[166:169], v[226:229], v[18:33]
	ds_read_b64_tr_b16 v[226:227], v246 offset:9728
	ds_read_b64_tr_b16 v[228:229], v246 offset:11776
	s_waitcnt lgkmcnt(6)
	v_mfma_f32_32x32x16_bf16 v[18:33], v[170:173], v[190:193], v[18:33]
	ds_read_b64_tr_b16 v[190:191], v246 offset:13824
	ds_read_b64_tr_b16 v[192:193], v246 offset:15872
	s_waitcnt lgkmcnt(6)
	v_mfma_f32_32x32x16_bf16 v[2:17], v[158:161], v[218:221], v[2:17]
	s_waitcnt lgkmcnt(4)
	v_mfma_f32_32x32x16_bf16 v[2:17], v[162:165], v[222:225], v[2:17]
	s_waitcnt lgkmcnt(2)
	v_mfma_f32_32x32x16_bf16 v[2:17], v[166:169], v[226:229], v[2:17]
	s_waitcnt lgkmcnt(0)
	v_mfma_f32_32x32x16_bf16 v[2:17], v[170:173], v[190:193], v[2:17]
	s_waitcnt vmcnt(0)
	s_barrier
